# GU epilogue v2: ai=1 rows first, next unit's first LDS fragment reads and LDS-DMA stage issued under the remaining epilogue math (on v16)
# speedup vs baseline: 1.0024x; 1.0009x over previous
; __device__ __forceinline__ bool order_mn(int L, int nM, int nN, int& pm, int& pn) {
;     const int nwg = nM * nN; if (L >= nwg) return false;
;     int wgid = L; { const int q = nwg / 8, r = nwg % 8, xcd = wgid % 8, off = wgid / 8; wgid = (xcd < r ? xcd * (q + 1) : r * (q + 1) + (xcd - r) * q) + off; }
;     const int nig = 8 * nN, gid = wgid / nig, fm = gid * 8, gsz = (nM - fm) < 8 ? (nM - fm) : 8;
;     pm = fm + ((wgid % nig) % gsz); pn = (wgid % nig) / gsz; return true;
; }
.Lgu_fp_229:
	s_waitcnt lgkmcnt(8)
	s_barrier
	s_waitcnt lgkmcnt(0)
	v_mfma_f32_16x16x32_bf16 v[48:51], v[0:3], v[16:19], 0
	s_add_i32 s46, s46, 1
	v_mfma_f32_16x16x32_bf16 v[52:55], v[8:11], v[16:19], 0
	s_mul_i32 s17, s46, s96
	v_mfma_f32_16x16x32_bf16 v[56:59], v[0:3], v[24:27], 0
	s_add_i32 s17, s17, s33
	v_mfma_f32_16x16x32_bf16 v[60:63], v[8:11], v[24:27], 0
	s_cmpk_lt_i32 s17, 0xb00
	v_mfma_f32_16x16x32_bf16 v[64:67], v[0:3], v[32:35], 0
	s_cselect_b64 s[30:31], -1, 0
	v_mfma_f32_16x16x32_bf16 v[68:71], v[8:11], v[32:35], 0
	s_cmpk_gt_i32 s17, 0xaff
	v_mfma_f32_16x16x32_bf16 v[72:75], v[0:3], v[40:43], 0
	s_cselect_b64 s[14:15], -1, 0
	v_mfma_f32_16x16x32_bf16 v[76:79], v[8:11], v[40:43], 0
	s_ashr_i32 s16, s17, 31
	v_mfma_f32_16x16x32_bf16 v[48:51], v[4:7], v[20:23], v[48:51]
	s_lshr_b32 s16, s16, 29
	v_mfma_f32_16x16x32_bf16 v[52:55], v[12:15], v[20:23], v[52:55]
	s_add_i32 s16, s17, s16
	v_mfma_f32_16x16x32_bf16 v[56:59], v[4:7], v[28:31], v[56:59]
	s_ashr_i32 s18, s16, 3
	v_mfma_f32_16x16x32_bf16 v[60:63], v[12:15], v[28:31], v[60:63]
	s_and_b32 s16, s16, -8
	v_mfma_f32_16x16x32_bf16 v[64:67], v[4:7], v[36:39], v[64:67]
	s_sub_i32 s16, s17, s16
	v_mfma_f32_16x16x32_bf16 v[68:71], v[12:15], v[36:39], v[68:71]
	s_lshr_b32 s17, s16, 31
	v_mfma_f32_16x16x32_bf16 v[72:75], v[4:7], v[44:47], v[72:75]
	s_or_b32 s17, s17, 0x160
	v_mfma_f32_16x16x32_bf16 v[76:79], v[12:15], v[44:47], v[76:79]
	s_barrier
	v_lshl_add_u64 v[218:219], s[28:29], 0, v[134:135]
	s_mov_b32 m0, s49
	v_lshl_add_u64 v[96:97], v[218:219], 0, s[8:9]
	v_lshl_add_u64 v[238:239], s[28:29], 0, v[130:131]
	ds_read_b128 v[80:83], v154
	ds_read_b128 v[84:87], v154 offset:1024
	ds_read_b128 v[88:91], v154 offset:2048
	ds_read_b128 v[92:95], v154 offset:3072
	global_load_lds_dwordx4 v[96:97], off
	s_mov_b32 m0, s50
	v_lshl_add_u64 v[96:97], v[238:239], 0, s[8:9]
	global_load_lds_dwordx4 v[96:97], off
	s_barrier
	s_waitcnt lgkmcnt(0)
	v_mfma_f32_16x16x32_bf16 v[96:99], v[80:83], v[16:19], 0
	s_mul_i32 s16, s17, s16
	v_mfma_f32_16x16x32_bf16 v[16:19], v[88:91], v[16:19], 0
	s_add_i32 s16, s16, s18
	v_mfma_f32_16x16x32_bf16 v[100:103], v[80:83], v[24:27], 0
	s_mul_hi_i32 s17, s16, 0x2e8ba2e9
	v_mfma_f32_16x16x32_bf16 v[24:27], v[88:91], v[24:27], 0
	s_lshr_b32 s18, s17, 31
	v_mfma_f32_16x16x32_bf16 v[104:107], v[80:83], v[32:35], 0
	s_ashr_i32 s17, s17, 5
	v_mfma_f32_16x16x32_bf16 v[32:35], v[88:91], v[32:35], 0
	s_add_i32 s17, s17, s18
	v_mfma_f32_16x16x32_bf16 v[108:111], v[80:83], v[40:43], 0
	s_lshl_b32 s18, s17, 3
	v_mfma_f32_16x16x32_bf16 v[40:43], v[88:91], v[40:43], 0
	s_sub_i32 s19, 0x80, s18
	v_mfma_f32_16x16x32_bf16 v[116:119], v[84:87], v[20:23], v[96:99]
	s_min_u32 s19, s19, 8
	v_mfma_f32_16x16x32_bf16 v[16:19], v[92:95], v[20:23], v[16:19]
	s_mulk_i32 s17, 0xb0
	v_mfma_f32_16x16x32_bf16 v[20:23], v[84:87], v[28:31], v[100:103]
	s_sub_i32 s20, s16, s17
	v_mfma_f32_16x16x32_bf16 v[24:27], v[92:95], v[28:31], v[24:27]
	v_cvt_f32_ubyte0_e32 v251, s19
	v_mfma_f32_16x16x32_bf16 v[28:31], v[84:87], v[36:39], v[104:107]
	v_cvt_f32_i32_e32 v250, s20
	v_mfma_f32_16x16x32_bf16 v[32:35], v[92:95], v[36:39], v[32:35]
	v_rcp_iflag_f32_e32 v252, v251
	v_mfma_f32_16x16x32_bf16 v[36:39], v[84:87], v[44:47], v[108:111]
	s_ashr_i32 s16, s20, 30
	v_mfma_f32_16x16x32_bf16 v[40:43], v[92:95], v[44:47], v[40:43]
	v_lshl_add_u64 v[246:247], s[26:27], 0, v[136:137]
	s_mov_b32 m0, s25
	v_lshl_add_u64 v[142:143], v[246:247], 0, s[8:9]
	v_lshl_add_u64 v[248:249], s[26:27], 0, v[132:133]
	s_barrier
	ds_read_b128 v[44:47], v153 offset:16384
	ds_read_b128 v[96:99], v153 offset:17408
	ds_read_b128 v[100:103], v153 offset:18432
	ds_read_b128 v[104:107], v153 offset:19456
	ds_read_b128 v[108:111], v153 offset:20480
	ds_read_b128 v[112:115], v153 offset:21504
	ds_read_b128 v[120:123], v153 offset:22528
	ds_read_b128 v[124:127], v153 offset:23552
	global_load_lds_dwordx4 v[142:143], off
	s_mov_b32 m0, s41
	v_lshl_add_u64 v[142:143], v[248:249], 0, s[8:9]
	global_load_lds_dwordx4 v[142:143], off
	s_barrier
	s_waitcnt lgkmcnt(0)
	v_mfma_f32_16x16x32_bf16 v[142:145], v[0:3], v[44:47], 0
	s_or_b32 s21, s16, 1
	v_mfma_f32_16x16x32_bf16 v[158:161], v[8:11], v[44:47], 0
	v_mul_f32_e32 v252, v250, v252
	v_mfma_f32_16x16x32_bf16 v[162:165], v[0:3], v[100:103], 0
	v_trunc_f32_e32 v252, v252
	v_mfma_f32_16x16x32_bf16 v[166:169], v[8:11], v[100:103], 0
	v_fma_f32 v250, -v252, v251, v250
	v_mfma_f32_16x16x32_bf16 v[170:173], v[0:3], v[108:111], 0
	v_cvt_i32_f32_e32 v252, v252
	v_mfma_f32_16x16x32_bf16 v[174:177], v[8:11], v[108:111], 0
	v_cmp_ge_f32_e64 s[16:17], |v250|, v251
	v_mfma_f32_16x16x32_bf16 v[0:3], v[0:3], v[120:123], 0
	s_and_b64 s[16:17], s[16:17], exec
	v_mfma_f32_16x16x32_bf16 v[8:11], v[8:11], v[120:123], 0
	s_cselect_b32 s16, s21, 0
	v_mfma_f32_16x16x32_bf16 v[142:145], v[4:7], v[96:99], v[142:145]
	v_readfirstlane_b32 s17, v252
	v_mfma_f32_16x16x32_bf16 v[162:165], v[4:7], v[104:107], v[162:165]
	s_add_i32 s17, s17, s16
	v_mfma_f32_16x16x32_bf16 v[170:173], v[4:7], v[112:115], v[170:173]
	s_sext_i32_i16 s16, s17
	v_mfma_f32_16x16x32_bf16 v[0:3], v[4:7], v[124:127], v[0:3]
	s_mul_i32 s17, s17, s19
	v_mfma_f32_16x16x32_bf16 v[4:7], v[12:15], v[124:127], v[8:11]
	s_sub_i32 s17, s20, s17
	v_mfma_f32_16x16x32_bf16 v[158:161], v[12:15], v[96:99], v[158:161]
	s_sext_i32_i16 s17, s17
	v_mfma_f32_16x16x32_bf16 v[166:169], v[12:15], v[104:107], v[166:169]
	s_add_i32 s18, s18, s17
	v_mfma_f32_16x16x32_bf16 v[174:177], v[12:15], v[112:115], v[174:177]
	s_barrier
	s_add_u32 s34, s28, 0x40100
	s_addc_u32 s35, s29, 0
	s_mov_b32 m0, s55
	v_lshl_add_u64 v[8:9], s[34:35], 0, v[134:135]
	global_load_lds_dwordx4 v[8:9], off
	s_mov_b32 m0, s56
	v_lshl_add_u64 v[8:9], s[34:35], 0, v[130:131]
	global_load_lds_dwordx4 v[8:9], off
	s_waitcnt vmcnt(6)
	s_barrier
	v_mfma_f32_16x16x32_bf16 v[8:11], v[80:83], v[44:47], 0
	s_ashr_i32 s19, s18, 31
	v_mfma_f32_16x16x32_bf16 v[12:15], v[88:91], v[44:47], 0
	s_lshl_b64 s[20:21], s[18:19], 19
	v_mfma_f32_16x16x32_bf16 v[44:47], v[80:83], v[100:103], 0
	s_add_u32 s20, s10, s20
	v_mfma_f32_16x16x32_bf16 v[100:103], v[88:91], v[100:103], 0
	s_addc_u32 s21, s11, s21
	v_mfma_f32_16x16x32_bf16 v[178:181], v[80:83], v[108:111], 0
	s_ashr_i32 s17, s16, 31
	v_mfma_f32_16x16x32_bf16 v[108:111], v[88:91], v[108:111], 0
	s_lshl_b64 s[22:23], s[16:17], 19
	v_mfma_f32_16x16x32_bf16 v[80:83], v[80:83], v[120:123], 0
	s_add_u32 s22, s39, s22
	v_mfma_f32_16x16x32_bf16 v[88:91], v[88:91], v[120:123], 0
	s_addc_u32 s23, s40, s23
	v_mfma_f32_16x16x32_bf16 v[12:15], v[92:95], v[96:99], v[12:15]
	v_mfma_f32_16x16x32_bf16 v[44:47], v[84:87], v[104:107], v[44:47]
	v_mfma_f32_16x16x32_bf16 v[182:185], v[84:87], v[96:99], v[8:11]
	v_mfma_f32_16x16x32_bf16 v[186:189], v[92:95], v[104:107], v[100:103]
	v_mfma_f32_16x16x32_bf16 v[178:181], v[84:87], v[112:115], v[178:181]
	v_mfma_f32_16x16x32_bf16 v[190:193], v[92:95], v[112:115], v[108:111]
	v_mfma_f32_16x16x32_bf16 v[194:197], v[84:87], v[124:127], v[80:83]
	v_mfma_f32_16x16x32_bf16 v[198:201], v[92:95], v[124:127], v[88:91]
	s_barrier
	ds_read_b128 v[8:11], v155
	ds_read_b128 v[202:205], v155 offset:1024
	ds_read_b128 v[206:209], v155 offset:2048
	ds_read_b128 v[210:213], v155 offset:3072
	s_add_u32 s34, s26, 0x40100
	s_addc_u32 s35, s27, 0
	s_mov_b32 m0, s42
	v_lshl_add_u64 v[80:81], s[34:35], 0, v[136:137]
	ds_read_b128 v[84:87], v153 offset:32768
	ds_read_b128 v[92:95], v153 offset:33792
	ds_read_b128 v[100:103], v153 offset:34816
	ds_read_b128 v[214:217], v153 offset:35840
	ds_read_b128 v[108:111], v153 offset:36864
	ds_read_b128 v[222:225], v153 offset:37888
	ds_read_b128 v[124:127], v153 offset:38912
	ds_read_b128 v[226:229], v153 offset:39936
	global_load_lds_dwordx4 v[80:81], off
	s_mov_b32 m0, s43
	v_lshl_add_u64 v[80:81], s[34:35], 0, v[132:133]
	global_load_lds_dwordx4 v[80:81], off
	s_waitcnt lgkmcnt(8)
	s_barrier
	s_waitcnt lgkmcnt(0)
	v_mfma_f32_16x16x32_bf16 v[48:51], v[8:11], v[84:87], v[48:51]
	v_mfma_f32_16x16x32_bf16 v[52:55], v[206:209], v[84:87], v[52:55]
	v_mfma_f32_16x16x32_bf16 v[56:59], v[8:11], v[100:103], v[56:59]
	v_mfma_f32_16x16x32_bf16 v[60:63], v[206:209], v[100:103], v[60:63]
	v_mfma_f32_16x16x32_bf16 v[64:67], v[8:11], v[108:111], v[64:67]
	v_mfma_f32_16x16x32_bf16 v[68:71], v[206:209], v[108:111], v[68:71]
	v_mfma_f32_16x16x32_bf16 v[72:75], v[8:11], v[124:127], v[72:75]
	v_mfma_f32_16x16x32_bf16 v[76:79], v[206:209], v[124:127], v[76:79]
	v_mfma_f32_16x16x32_bf16 v[120:123], v[202:205], v[92:95], v[48:51]
	v_mfma_f32_16x16x32_bf16 v[112:115], v[210:213], v[92:95], v[52:55]
	v_mfma_f32_16x16x32_bf16 v[104:107], v[202:205], v[214:217], v[56:59]
	v_mfma_f32_16x16x32_bf16 v[96:99], v[210:213], v[214:217], v[60:63]
	v_mfma_f32_16x16x32_bf16 v[88:91], v[202:205], v[222:225], v[64:67]
	v_mfma_f32_16x16x32_bf16 v[80:83], v[210:213], v[222:225], v[68:71]
	v_mfma_f32_16x16x32_bf16 v[72:75], v[202:205], v[226:229], v[72:75]
	v_mfma_f32_16x16x32_bf16 v[60:63], v[210:213], v[226:229], v[76:79]
	s_barrier
	s_mov_b32 m0, s57
	v_lshl_add_u64 v[48:49], v[218:219], 0, s[12:13]
	ds_read_b128 v[52:55], v156
	ds_read_b128 v[230:233], v156 offset:1024
	ds_read_b128 v[68:71], v156 offset:2048
	ds_read_b128 v[234:237], v156 offset:3072
	global_load_lds_dwordx4 v[48:49], off
	s_mov_b32 m0, s58
	v_lshl_add_u64 v[48:49], v[238:239], 0, s[12:13]
	global_load_lds_dwordx4 v[48:49], off
	s_barrier
	s_waitcnt lgkmcnt(0)
	v_mfma_f32_16x16x32_bf16 v[48:51], v[52:55], v[84:87], v[116:119]
	v_mfma_f32_16x16x32_bf16 v[16:19], v[68:71], v[84:87], v[16:19]
	v_mfma_f32_16x16x32_bf16 v[20:23], v[52:55], v[100:103], v[20:23]
	v_mfma_f32_16x16x32_bf16 v[24:27], v[68:71], v[100:103], v[24:27]
	v_mfma_f32_16x16x32_bf16 v[28:31], v[52:55], v[108:111], v[28:31]
	v_mfma_f32_16x16x32_bf16 v[32:35], v[68:71], v[108:111], v[32:35]
	v_mfma_f32_16x16x32_bf16 v[36:39], v[52:55], v[124:127], v[36:39]
	v_mfma_f32_16x16x32_bf16 v[40:43], v[68:71], v[124:127], v[40:43]
	v_mfma_f32_16x16x32_bf16 v[124:127], v[230:233], v[92:95], v[48:51]
	v_mfma_f32_16x16x32_bf16 v[116:119], v[234:237], v[92:95], v[16:19]
	v_mfma_f32_16x16x32_bf16 v[108:111], v[230:233], v[214:217], v[20:23]
	v_mfma_f32_16x16x32_bf16 v[100:103], v[234:237], v[214:217], v[24:27]
	v_mfma_f32_16x16x32_bf16 v[92:95], v[230:233], v[222:225], v[28:31]
	v_mfma_f32_16x16x32_bf16 v[84:87], v[234:237], v[222:225], v[32:35]
	v_mfma_f32_16x16x32_bf16 v[76:79], v[230:233], v[226:229], v[36:39]
	v_mfma_f32_16x16x32_bf16 v[64:67], v[234:237], v[226:229], v[40:43]
	s_mov_b32 m0, s44
	v_lshl_add_u64 v[16:17], v[246:247], 0, s[12:13]
	s_barrier
	ds_read_b128 v[20:23], v153 offset:49152
	ds_read_b128 v[28:31], v153 offset:50176
	ds_read_b128 v[36:39], v153 offset:51200
	ds_read_b128 v[214:217], v153 offset:52224
	ds_read_b128 v[222:225], v153 offset:53248
	ds_read_b128 v[226:229], v153 offset:54272
	ds_read_b128 v[238:241], v153 offset:55296
	ds_read_b128 v[242:245], v153 offset:56320
	global_load_lds_dwordx4 v[16:17], off
	s_mov_b32 m0, s45
	v_lshl_add_u64 v[16:17], v[248:249], 0, s[12:13]
	global_load_lds_dwordx4 v[16:17], off
	s_barrier
	s_waitcnt lgkmcnt(0)
	v_mfma_f32_16x16x32_bf16 v[16:19], v[8:11], v[20:23], v[142:145]
	v_mfma_f32_16x16x32_bf16 v[24:27], v[206:209], v[20:23], v[158:161]
	v_mfma_f32_16x16x32_bf16 v[32:35], v[8:11], v[36:39], v[162:165]
	v_mfma_f32_16x16x32_bf16 v[142:145], v[206:209], v[36:39], v[166:169]
	v_mfma_f32_16x16x32_bf16 v[158:161], v[8:11], v[222:225], v[170:173]
	v_mfma_f32_16x16x32_bf16 v[162:165], v[206:209], v[222:225], v[174:177]
	v_mfma_f32_16x16x32_bf16 v[0:3], v[8:11], v[238:241], v[0:3]
	v_mfma_f32_16x16x32_bf16 v[4:7], v[206:209], v[238:241], v[4:7]
	v_mfma_f32_16x16x32_bf16 v[56:59], v[202:205], v[28:31], v[16:19]
	v_mfma_f32_16x16x32_bf16 v[48:51], v[210:213], v[28:31], v[24:27]
	v_mfma_f32_16x16x32_bf16 v[40:43], v[202:205], v[214:217], v[32:35]
	v_mfma_f32_16x16x32_bf16 v[32:35], v[210:213], v[214:217], v[142:145]
	v_mfma_f32_16x16x32_bf16 v[24:27], v[202:205], v[226:229], v[158:161]
	v_mfma_f32_16x16x32_bf16 v[16:19], v[210:213], v[226:229], v[162:165]
	v_mfma_f32_16x16x32_bf16 v[8:11], v[202:205], v[242:245], v[0:3]
	v_mfma_f32_16x16x32_bf16 v[0:3], v[210:213], v[242:245], v[4:7]
	s_barrier
	s_add_u32 s34, s28, 0x40180
	s_addc_u32 s35, s29, 0
	s_mov_b32 m0, s59
	v_lshl_add_u64 v[4:5], s[34:35], 0, v[134:135]
	s_add_i32 s17, s59, 0x2000
	global_load_lds_dwordx4 v[4:5], off
	v_lshl_add_u64 v[4:5], s[34:35], 0, v[130:131]
	s_mov_b32 m0, s17
	s_mov_b64 s[34:35], 0x40180
	global_load_lds_dwordx4 v[4:5], off
	s_waitcnt vmcnt(6)
	s_barrier
	v_mfma_f32_16x16x32_bf16 v[4:7], v[52:55], v[20:23], v[182:185]
	v_mfma_f32_16x16x32_bf16 v[12:15], v[68:71], v[20:23], v[12:15]
	v_mfma_f32_16x16x32_bf16 v[20:23], v[52:55], v[36:39], v[44:47]
	v_mfma_f32_16x16x32_bf16 v[36:39], v[68:71], v[36:39], v[186:189]
	v_mfma_f32_16x16x32_bf16 v[142:145], v[52:55], v[222:225], v[178:181]
	v_mfma_f32_16x16x32_bf16 v[158:161], v[68:71], v[222:225], v[190:193]
	v_mfma_f32_16x16x32_bf16 v[162:165], v[52:55], v[238:241], v[194:197]
	v_mfma_f32_16x16x32_bf16 v[166:169], v[68:71], v[238:241], v[198:201]
	v_mfma_f32_16x16x32_bf16 v[68:71], v[230:233], v[28:31], v[4:7]
	v_mfma_f32_16x16x32_bf16 v[52:55], v[234:237], v[28:31], v[12:15]
	v_mfma_f32_16x16x32_bf16 v[44:47], v[230:233], v[214:217], v[20:23]
	v_mfma_f32_16x16x32_bf16 v[36:39], v[234:237], v[214:217], v[36:39]
	v_mfma_f32_16x16x32_bf16 v[28:31], v[230:233], v[226:229], v[142:145]
	v_mfma_f32_16x16x32_bf16 v[20:23], v[234:237], v[226:229], v[158:161]
	v_mfma_f32_16x16x32_bf16 v[12:15], v[230:233], v[242:245], v[162:165]
	v_mfma_f32_16x16x32_bf16 v[4:7], v[234:237], v[242:245], v[166:169]
	v_lshl_add_u64 v[142:143], s[26:27], 0, v[138:139]
	v_lshl_add_u64 v[144:145], s[26:27], 0, v[140:141]
	s_mov_b32 s19, 0

.LBB0_232:
	ds_read_b128 v[158:161], v152
	ds_read_b128 v[162:165], v152 offset:1024
	ds_read_b128 v[166:169], v152 offset:2048
	ds_read_b128 v[170:173], v152 offset:3072
	s_mov_b32 m0, s47
	v_lshl_add_u64 v[206:207], v[142:143], 0, s[34:35]
	ds_read_b128 v[174:177], v153
	ds_read_b128 v[178:181], v153 offset:1024
	ds_read_b128 v[182:185], v153 offset:2048
	ds_read_b128 v[186:189], v153 offset:3072
	ds_read_b128 v[190:193], v153 offset:4096
	ds_read_b128 v[194:197], v153 offset:5120
	ds_read_b128 v[198:201], v153 offset:6144
	ds_read_b128 v[202:205], v153 offset:7168
	global_load_lds_dwordx4 v[206:207], off
	s_mov_b32 m0, s48
	v_lshl_add_u64 v[206:207], v[144:145], 0, s[34:35]
	global_load_lds_dwordx4 v[206:207], off
	s_waitcnt lgkmcnt(8)
	s_barrier
	s_waitcnt lgkmcnt(0)
	v_mfma_f32_16x16x32_bf16 v[120:123], v[158:161], v[174:177], v[120:123]
	s_add_i32 s61, s34, 0xfffc0080
	v_mfma_f32_16x16x32_bf16 v[112:115], v[166:169], v[174:177], v[112:115]
	s_cmp_eq_u32 s19, 12
	v_mfma_f32_16x16x32_bf16 v[104:107], v[158:161], v[182:185], v[104:107]
	s_cselect_b64 s[36:37], -1, 0
	v_mfma_f32_16x16x32_bf16 v[96:99], v[166:169], v[182:185], v[96:99]
	s_and_b64 s[62:63], s[36:37], exec
	v_mfma_f32_16x16x32_bf16 v[88:91], v[158:161], v[190:193], v[88:91]
	s_cselect_b32 s61, 0, s61
	v_mfma_f32_16x16x32_bf16 v[80:83], v[166:169], v[190:193], v[80:83]
	s_and_b64 s[36:37], s[30:31], s[36:37]
	v_mfma_f32_16x16x32_bf16 v[72:75], v[158:161], v[198:201], v[72:75]
	s_and_b64 s[36:37], s[36:37], exec
	v_mfma_f32_16x16x32_bf16 v[60:63], v[166:169], v[198:201], v[60:63]
	s_cselect_b32 s63, s21, s27
	v_mfma_f32_16x16x32_bf16 v[120:123], v[162:165], v[178:181], v[120:123]
	s_cselect_b32 s62, s20, s26
	v_mfma_f32_16x16x32_bf16 v[112:115], v[170:173], v[178:181], v[112:115]
	s_cselect_b32 s37, s23, s29
	v_mfma_f32_16x16x32_bf16 v[104:107], v[162:165], v[186:189], v[104:107]
	s_cselect_b32 s36, s22, s28
	v_mfma_f32_16x16x32_bf16 v[96:99], v[170:173], v[186:189], v[96:99]
	v_mfma_f32_16x16x32_bf16 v[88:91], v[162:165], v[194:197], v[88:91]
	v_mfma_f32_16x16x32_bf16 v[80:83], v[170:173], v[194:197], v[80:83]
	v_mfma_f32_16x16x32_bf16 v[72:75], v[162:165], v[202:205], v[72:75]
	v_mfma_f32_16x16x32_bf16 v[60:63], v[170:173], v[202:205], v[60:63]
	s_barrier
	s_add_u32 s36, s36, s61
	s_addc_u32 s37, s37, 0
	s_mov_b32 m0, s49
	v_lshl_add_u64 v[218:219], s[36:37], 0, v[134:135]
	ds_read_b128 v[206:209], v154
	ds_read_b128 v[210:213], v154 offset:1024
	ds_read_b128 v[214:217], v154 offset:2048
	ds_read_b128 v[222:225], v154 offset:3072
	global_load_lds_dwordx4 v[218:219], off
	s_mov_b32 m0, s50
	v_lshl_add_u64 v[226:227], s[36:37], 0, v[130:131]
	global_load_lds_dwordx4 v[226:227], off
	s_barrier
	s_waitcnt lgkmcnt(0)
	v_mfma_f32_16x16x32_bf16 v[124:127], v[206:209], v[174:177], v[124:127]
	v_mfma_f32_16x16x32_bf16 v[116:119], v[214:217], v[174:177], v[116:119]
	v_mfma_f32_16x16x32_bf16 v[108:111], v[206:209], v[182:185], v[108:111]
	v_mfma_f32_16x16x32_bf16 v[100:103], v[214:217], v[182:185], v[100:103]
	v_mfma_f32_16x16x32_bf16 v[92:95], v[206:209], v[190:193], v[92:95]
	v_mfma_f32_16x16x32_bf16 v[84:87], v[214:217], v[190:193], v[84:87]
	v_mfma_f32_16x16x32_bf16 v[76:79], v[206:209], v[198:201], v[76:79]
	v_mfma_f32_16x16x32_bf16 v[64:67], v[214:217], v[198:201], v[64:67]
	v_mfma_f32_16x16x32_bf16 v[124:127], v[210:213], v[178:181], v[124:127]
	v_mfma_f32_16x16x32_bf16 v[116:119], v[222:225], v[178:181], v[116:119]
	v_mfma_f32_16x16x32_bf16 v[108:111], v[210:213], v[186:189], v[108:111]
	v_mfma_f32_16x16x32_bf16 v[100:103], v[222:225], v[186:189], v[100:103]
	v_mfma_f32_16x16x32_bf16 v[92:95], v[210:213], v[194:197], v[92:95]
	v_mfma_f32_16x16x32_bf16 v[84:87], v[222:225], v[194:197], v[84:87]
	v_mfma_f32_16x16x32_bf16 v[76:79], v[210:213], v[202:205], v[76:79]
	v_mfma_f32_16x16x32_bf16 v[64:67], v[222:225], v[202:205], v[64:67]
	s_add_u32 s62, s62, s61
	s_addc_u32 s63, s63, 0
	s_mov_b32 m0, s25
	v_lshl_add_u64 v[228:229], s[62:63], 0, v[136:137]
	s_barrier
	ds_read_b128 v[174:177], v153 offset:16384
	ds_read_b128 v[178:181], v153 offset:17408
	ds_read_b128 v[182:185], v153 offset:18432
	ds_read_b128 v[186:189], v153 offset:19456
	ds_read_b128 v[190:193], v153 offset:20480
	ds_read_b128 v[194:197], v153 offset:21504
	ds_read_b128 v[198:201], v153 offset:22528
	ds_read_b128 v[202:205], v153 offset:23552
	global_load_lds_dwordx4 v[228:229], off
	s_mov_b32 m0, s41
	v_lshl_add_u64 v[230:231], s[62:63], 0, v[132:133]
	global_load_lds_dwordx4 v[230:231], off
	s_barrier
	s_waitcnt lgkmcnt(0)
	v_mfma_f32_16x16x32_bf16 v[56:59], v[158:161], v[174:177], v[56:59]
	v_mfma_f32_16x16x32_bf16 v[48:51], v[166:169], v[174:177], v[48:51]
	v_mfma_f32_16x16x32_bf16 v[40:43], v[158:161], v[182:185], v[40:43]
	v_mfma_f32_16x16x32_bf16 v[32:35], v[166:169], v[182:185], v[32:35]
	v_mfma_f32_16x16x32_bf16 v[24:27], v[158:161], v[190:193], v[24:27]
	v_mfma_f32_16x16x32_bf16 v[16:19], v[166:169], v[190:193], v[16:19]
	v_mfma_f32_16x16x32_bf16 v[8:11], v[158:161], v[198:201], v[8:11]
	v_mfma_f32_16x16x32_bf16 v[0:3], v[166:169], v[198:201], v[0:3]
	v_mfma_f32_16x16x32_bf16 v[56:59], v[162:165], v[178:181], v[56:59]
	v_mfma_f32_16x16x32_bf16 v[48:51], v[170:173], v[178:181], v[48:51]
	v_mfma_f32_16x16x32_bf16 v[40:43], v[162:165], v[186:189], v[40:43]
	v_mfma_f32_16x16x32_bf16 v[32:35], v[170:173], v[186:189], v[32:35]
	v_mfma_f32_16x16x32_bf16 v[24:27], v[162:165], v[194:197], v[24:27]
	v_mfma_f32_16x16x32_bf16 v[16:19], v[170:173], v[194:197], v[16:19]
	v_mfma_f32_16x16x32_bf16 v[8:11], v[162:165], v[202:205], v[8:11]
	v_mfma_f32_16x16x32_bf16 v[0:3], v[170:173], v[202:205], v[0:3]
	s_barrier
	s_add_u32 s64, s36, 0x40000
	s_addc_u32 s65, s37, 0
	s_mov_b32 m0, s55
	v_lshl_add_u64 v[158:159], s[64:65], 0, v[134:135]
	global_load_lds_dwordx4 v[158:159], off
	s_mov_b32 m0, s56
	v_lshl_add_u64 v[158:159], s[64:65], 0, v[130:131]
	global_load_lds_dwordx4 v[158:159], off
	s_waitcnt vmcnt(6)
	s_barrier
	v_mfma_f32_16x16x32_bf16 v[68:71], v[206:209], v[174:177], v[68:71]
	v_mfma_f32_16x16x32_bf16 v[52:55], v[214:217], v[174:177], v[52:55]
	v_mfma_f32_16x16x32_bf16 v[44:47], v[206:209], v[182:185], v[44:47]
	v_mfma_f32_16x16x32_bf16 v[36:39], v[214:217], v[182:185], v[36:39]
	v_mfma_f32_16x16x32_bf16 v[28:31], v[206:209], v[190:193], v[28:31]
	v_mfma_f32_16x16x32_bf16 v[20:23], v[214:217], v[190:193], v[20:23]
	v_mfma_f32_16x16x32_bf16 v[12:15], v[206:209], v[198:201], v[12:15]
	v_mfma_f32_16x16x32_bf16 v[4:7], v[214:217], v[198:201], v[4:7]
	v_mfma_f32_16x16x32_bf16 v[68:71], v[210:213], v[178:181], v[68:71]
	v_mfma_f32_16x16x32_bf16 v[52:55], v[222:225], v[178:181], v[52:55]
	v_mfma_f32_16x16x32_bf16 v[44:47], v[210:213], v[186:189], v[44:47]
	v_mfma_f32_16x16x32_bf16 v[36:39], v[222:225], v[186:189], v[36:39]
	v_mfma_f32_16x16x32_bf16 v[28:31], v[210:213], v[194:197], v[28:31]
	v_mfma_f32_16x16x32_bf16 v[20:23], v[222:225], v[194:197], v[20:23]
	v_mfma_f32_16x16x32_bf16 v[12:15], v[210:213], v[202:205], v[12:15]
	v_mfma_f32_16x16x32_bf16 v[4:7], v[222:225], v[202:205], v[4:7]
	s_barrier
	ds_read_b128 v[158:161], v155
	ds_read_b128 v[162:165], v155 offset:1024
	ds_read_b128 v[166:169], v155 offset:2048
	ds_read_b128 v[170:173], v155 offset:3072
	s_add_u32 s62, s62, 0x40000
	s_addc_u32 s63, s63, 0
	s_mov_b32 m0, s42
	v_lshl_add_u64 v[206:207], s[62:63], 0, v[136:137]
	ds_read_b128 v[174:177], v153 offset:32768
	ds_read_b128 v[178:181], v153 offset:33792
	ds_read_b128 v[182:185], v153 offset:34816
	ds_read_b128 v[186:189], v153 offset:35840
	ds_read_b128 v[190:193], v153 offset:36864
	ds_read_b128 v[194:197], v153 offset:37888
	ds_read_b128 v[198:201], v153 offset:38912
	ds_read_b128 v[202:205], v153 offset:39936
	global_load_lds_dwordx4 v[206:207], off
	s_mov_b32 m0, s43
	v_lshl_add_u64 v[206:207], s[62:63], 0, v[132:133]
	global_load_lds_dwordx4 v[206:207], off
	s_waitcnt lgkmcnt(8)
	s_barrier
	s_waitcnt lgkmcnt(0)
	v_mfma_f32_16x16x32_bf16 v[120:123], v[158:161], v[174:177], v[120:123]
	v_mfma_f32_16x16x32_bf16 v[112:115], v[166:169], v[174:177], v[112:115]
	v_mfma_f32_16x16x32_bf16 v[104:107], v[158:161], v[182:185], v[104:107]
	v_mfma_f32_16x16x32_bf16 v[96:99], v[166:169], v[182:185], v[96:99]
	v_mfma_f32_16x16x32_bf16 v[88:91], v[158:161], v[190:193], v[88:91]
	v_mfma_f32_16x16x32_bf16 v[80:83], v[166:169], v[190:193], v[80:83]
	v_mfma_f32_16x16x32_bf16 v[72:75], v[158:161], v[198:201], v[72:75]
	v_mfma_f32_16x16x32_bf16 v[60:63], v[166:169], v[198:201], v[60:63]
	v_mfma_f32_16x16x32_bf16 v[120:123], v[162:165], v[178:181], v[120:123]
	v_mfma_f32_16x16x32_bf16 v[112:115], v[170:173], v[178:181], v[112:115]
	v_mfma_f32_16x16x32_bf16 v[104:107], v[162:165], v[186:189], v[104:107]
	v_mfma_f32_16x16x32_bf16 v[96:99], v[170:173], v[186:189], v[96:99]
	v_mfma_f32_16x16x32_bf16 v[88:91], v[162:165], v[194:197], v[88:91]
	v_mfma_f32_16x16x32_bf16 v[80:83], v[170:173], v[194:197], v[80:83]
	v_mfma_f32_16x16x32_bf16 v[72:75], v[162:165], v[202:205], v[72:75]
	v_mfma_f32_16x16x32_bf16 v[60:63], v[170:173], v[202:205], v[60:63]
	s_barrier
	s_mov_b32 m0, s57
	v_lshl_add_u64 v[218:219], v[218:219], 0, s[6:7]
	ds_read_b128 v[206:209], v156
	ds_read_b128 v[210:213], v156 offset:1024
	ds_read_b128 v[214:217], v156 offset:2048
	ds_read_b128 v[222:225], v156 offset:3072
	global_load_lds_dwordx4 v[218:219], off
	s_mov_b32 m0, s58
	v_lshl_add_u64 v[218:219], v[226:227], 0, s[6:7]
	global_load_lds_dwordx4 v[218:219], off
	s_barrier
	s_waitcnt lgkmcnt(0)
	v_mfma_f32_16x16x32_bf16 v[124:127], v[206:209], v[174:177], v[124:127]
	v_mfma_f32_16x16x32_bf16 v[116:119], v[214:217], v[174:177], v[116:119]
	v_mfma_f32_16x16x32_bf16 v[108:111], v[206:209], v[182:185], v[108:111]
	v_mfma_f32_16x16x32_bf16 v[100:103], v[214:217], v[182:185], v[100:103]
	v_mfma_f32_16x16x32_bf16 v[92:95], v[206:209], v[190:193], v[92:95]
	v_mfma_f32_16x16x32_bf16 v[84:87], v[214:217], v[190:193], v[84:87]
	v_mfma_f32_16x16x32_bf16 v[76:79], v[206:209], v[198:201], v[76:79]
	v_mfma_f32_16x16x32_bf16 v[64:67], v[214:217], v[198:201], v[64:67]
	v_mfma_f32_16x16x32_bf16 v[124:127], v[210:213], v[178:181], v[124:127]
	v_mfma_f32_16x16x32_bf16 v[116:119], v[222:225], v[178:181], v[116:119]
	v_mfma_f32_16x16x32_bf16 v[108:111], v[210:213], v[186:189], v[108:111]
	v_mfma_f32_16x16x32_bf16 v[100:103], v[222:225], v[186:189], v[100:103]
	v_mfma_f32_16x16x32_bf16 v[92:95], v[210:213], v[194:197], v[92:95]
	v_mfma_f32_16x16x32_bf16 v[84:87], v[222:225], v[194:197], v[84:87]
	v_mfma_f32_16x16x32_bf16 v[76:79], v[210:213], v[202:205], v[76:79]
	v_mfma_f32_16x16x32_bf16 v[64:67], v[222:225], v[202:205], v[64:67]
	s_mov_b32 m0, s44
	v_lshl_add_u64 v[218:219], v[228:229], 0, s[6:7]
	s_barrier
	ds_read_b128 v[174:177], v153 offset:49152
	ds_read_b128 v[178:181], v153 offset:50176
	ds_read_b128 v[182:185], v153 offset:51200
	ds_read_b128 v[186:189], v153 offset:52224
	ds_read_b128 v[190:193], v153 offset:53248
	ds_read_b128 v[194:197], v153 offset:54272
	ds_read_b128 v[198:201], v153 offset:55296
	ds_read_b128 v[202:205], v153 offset:56320
	global_load_lds_dwordx4 v[218:219], off
	s_mov_b32 m0, s45
	v_lshl_add_u64 v[218:219], v[230:231], 0, s[6:7]
	global_load_lds_dwordx4 v[218:219], off
	s_barrier
; __device__ __forceinline__ unsigned pk2(float lo, float hi) { unsigned r; asm volatile("v_cvt_pk_bf16_f32 %0, %1, %2" : "=v"(r) : "v"(lo), "v"(hi)); return r; }
; __device__ __forceinline__ unsigned pk2(float lo, float hi) { return f2bf(lo) | (f2bf(hi) << 16); }
;     ...
;         G_PAIR(0, 1);
; #pragma unroll 1
;         for (int t = 2; t < nt; t += 2) G_PAIR(t, 0);
;         p.epi(acc, cur, wr, wc, fr, fq);
;     __device__ __forceinline__ void epi(const f32x4 (&acc)[2][2][4][2], const Unit& u, int wr, int wc, int fr, int fq) const {
;     ...
;         const int row0 = u.pm * 256 + wr * 64 + fr, col0 = u.pn * 128 + wc * 32 + 8 * fq;
; #pragma unroll
;         for (int ai = 0; ai < 2; ++ai)
; #pragma unroll
;             for (int m = 0; m < 4; ++m) {
;                 const int row = row0 + ai * 128 + m * 16; const float rs = rs_lds[((u.pm >> 3) & 1) * 256 + (row & 255)];
;                 const float rs2 = rs * -1.4426950408889634f, rsq = rs * rs;
;                 f32x2 v[4];
; #pragma unroll
;                 for (int n = 0; n < 2; ++n)
; #pragma unroll
;                     for (int jp = 0; jp < 2; ++jp) {
;                         const f32x2 gg = (f32x2){acc[ai][0][m][n][2 * jp], acc[ai][0][m][n][2 * jp + 1]}, uu = (f32x2){acc[ai][1][m][n][2 * jp], acc[ai][1][m][n][2 * jp + 1]};
;                         const f32x2 t = gg * rs2; f32x2 e; e.x = __builtin_amdgcn_exp2f(t.x); e.y = __builtin_amdgcn_exp2f(t.y);
;                         const f32x2 d = e + 1.0f; f32x2 r; r.x = __builtin_amdgcn_rcpf(d.x); r.y = __builtin_amdgcn_rcpf(d.y);
;                         v[n * 2 + jp] = (gg * uu) * (r * rsq);
;                     }
;                 u32x4 w; w.x = pk2(v[0].x, v[0].y); w.y = pk2(v[1].x, v[1].y); w.z = pk2(v[2].x, v[2].y); w.w = pk2(v[3].x, v[3].y);
;                 *(u32x4*)(H + (size_t)row * FF + col0) = w;
	s_waitcnt lgkmcnt(0)
	v_mfma_f32_16x16x32_bf16 v[56:59], v[158:161], v[174:177], v[56:59]
	v_mfma_f32_16x16x32_bf16 v[48:51], v[166:169], v[174:177], v[48:51]
	v_mfma_f32_16x16x32_bf16 v[40:43], v[158:161], v[182:185], v[40:43]
	v_mfma_f32_16x16x32_bf16 v[32:35], v[166:169], v[182:185], v[32:35]
	v_mfma_f32_16x16x32_bf16 v[24:27], v[158:161], v[190:193], v[24:27]
	v_mfma_f32_16x16x32_bf16 v[16:19], v[166:169], v[190:193], v[16:19]
	v_mfma_f32_16x16x32_bf16 v[8:11], v[158:161], v[198:201], v[8:11]
	v_mfma_f32_16x16x32_bf16 v[0:3], v[166:169], v[198:201], v[0:3]
	v_mfma_f32_16x16x32_bf16 v[56:59], v[162:165], v[178:181], v[56:59]
	v_mfma_f32_16x16x32_bf16 v[48:51], v[170:173], v[178:181], v[48:51]
	v_mfma_f32_16x16x32_bf16 v[40:43], v[162:165], v[186:189], v[40:43]
	v_mfma_f32_16x16x32_bf16 v[32:35], v[170:173], v[186:189], v[32:35]
	v_mfma_f32_16x16x32_bf16 v[24:27], v[162:165], v[194:197], v[24:27]
	v_mfma_f32_16x16x32_bf16 v[16:19], v[170:173], v[194:197], v[16:19]
	v_mfma_f32_16x16x32_bf16 v[8:11], v[162:165], v[202:205], v[8:11]
	v_mfma_f32_16x16x32_bf16 v[0:3], v[170:173], v[202:205], v[0:3]
	s_barrier
	s_add_u32 s36, s36, 0x40080
	s_addc_u32 s37, s37, 0
	s_mov_b32 m0, s59
	v_lshl_add_u64 v[158:159], s[36:37], 0, v[134:135]
	global_load_lds_dwordx4 v[158:159], off
	s_mov_b32 m0, s17
	v_lshl_add_u64 v[158:159], s[36:37], 0, v[130:131]
	global_load_lds_dwordx4 v[158:159], off
	s_waitcnt vmcnt(6)
	s_barrier
	v_mfma_f32_16x16x32_bf16 v[68:71], v[206:209], v[174:177], v[68:71]
	v_mfma_f32_16x16x32_bf16 v[52:55], v[214:217], v[174:177], v[52:55]
	v_mfma_f32_16x16x32_bf16 v[44:47], v[206:209], v[182:185], v[44:47]
	v_mfma_f32_16x16x32_bf16 v[36:39], v[214:217], v[182:185], v[36:39]
	v_mfma_f32_16x16x32_bf16 v[28:31], v[206:209], v[190:193], v[28:31]
	v_mfma_f32_16x16x32_bf16 v[20:23], v[214:217], v[190:193], v[20:23]
	v_mfma_f32_16x16x32_bf16 v[12:15], v[206:209], v[198:201], v[12:15]
	v_mfma_f32_16x16x32_bf16 v[4:7], v[214:217], v[198:201], v[4:7]
	v_mfma_f32_16x16x32_bf16 v[68:71], v[210:213], v[178:181], v[68:71]
	v_mfma_f32_16x16x32_bf16 v[52:55], v[222:225], v[178:181], v[52:55]
	v_mfma_f32_16x16x32_bf16 v[44:47], v[210:213], v[186:189], v[44:47]
	v_mfma_f32_16x16x32_bf16 v[36:39], v[222:225], v[186:189], v[36:39]
	v_mfma_f32_16x16x32_bf16 v[28:31], v[210:213], v[194:197], v[28:31]
	v_mfma_f32_16x16x32_bf16 v[20:23], v[222:225], v[194:197], v[20:23]
	v_mfma_f32_16x16x32_bf16 v[12:15], v[210:213], v[202:205], v[12:15]
	v_mfma_f32_16x16x32_bf16 v[4:7], v[222:225], v[202:205], v[4:7]
	s_add_i32 s19, s19, 2
	s_add_u32 s34, s34, 0x100
	s_addc_u32 s35, s35, 0
	s_cmp_gt_u32 s19, 13
	s_cbranch_scc0 .Lrot_232
	s_barrier
	s_lshl_b32 s17, s24, 7
	s_and_b32 s17, s17, 0x400
	s_add_i32 s17, s17, 0x20000
	v_lshl_add_u32 v142, v151, 2, s17
	ds_read_b32 v143, v142 offset:512
	v_lshl_add_u32 v172, s24, 8, v129
	v_lshl_or_b32 v174, s60, 7, v150
	v_mov_b64_e32 v[176:177], s[2:3]
	v_ashrrev_i32_e32 v175, 31, v174
	v_mad_i64_i32 v[166:167], s[26:27], v172, s51, v[176:177]
	v_lshlrev_b64 v[174:175], 1, v[174:175]
	v_mov_b32_e32 v172, 0xb0000
	v_mov_b32_e32 v173, 0
	v_lshl_add_u64 v[166:167], v[166:167], 0, v[174:175]
	v_mov_b32_e32 v168, 0x16000
	v_mov_b32_e32 v169, 0
	v_lshl_add_u64 v[170:171], v[166:167], 0, v[172:173]
	s_mov_b32 s60, s16
	s_mov_b32 s24, s18
	s_waitcnt lgkmcnt(0)
	v_mul_f32_e32 v144, 0xbfb8aa3b, v143
	v_mul_f32_e32 v164, v143, v143
	ds_read_b32 v143, v142 offset:576
	v_pk_mul_f32 v[160:161], v[56:57], v[144:145] op_sel_hi:[1,0]
	v_pk_mul_f32 v[162:163], v[58:59], v[144:145] op_sel_hi:[1,0]
	v_exp_f32_e32 v160, v160
	v_exp_f32_e32 v161, v161
	v_exp_f32_e32 v162, v162
	v_exp_f32_e32 v163, v163
	v_pk_mul_f32 v[56:57], v[56:57], v[68:69]
	v_pk_add_f32 v[160:161], v[160:161], 1.0 op_sel_hi:[1,0]
	v_pk_mul_f32 v[58:59], v[58:59], v[70:71]
	v_pk_add_f32 v[162:163], v[162:163], 1.0 op_sel_hi:[1,0]
	v_rcp_f32_e32 v160, v160
	v_rcp_f32_e32 v161, v161
	v_rcp_f32_e32 v162, v162
	v_rcp_f32_e32 v163, v163
	v_pk_mul_f32 v[160:161], v[164:165], v[160:161] op_sel_hi:[0,1]
	v_pk_mul_f32 v[56:57], v[56:57], v[160:161]
	v_pk_mul_f32 v[162:163], v[164:165], v[162:163] op_sel_hi:[0,1]
	v_pk_mul_f32 v[58:59], v[58:59], v[162:163]
	v_pk_mul_f32 v[160:161], v[48:49], v[144:145] op_sel_hi:[1,0]
	v_pk_mul_f32 v[162:163], v[50:51], v[144:145] op_sel_hi:[1,0]
	v_exp_f32_e32 v160, v160
	v_exp_f32_e32 v161, v161
	v_exp_f32_e32 v162, v162
	v_exp_f32_e32 v163, v163
	v_pk_mul_f32 v[48:49], v[48:49], v[52:53]
	v_pk_add_f32 v[160:161], v[160:161], 1.0 op_sel_hi:[1,0]
	v_pk_mul_f32 v[50:51], v[50:51], v[54:55]
	v_pk_add_f32 v[162:163], v[162:163], 1.0 op_sel_hi:[1,0]
	v_rcp_f32_e32 v160, v160
	v_rcp_f32_e32 v161, v161
	v_rcp_f32_e32 v162, v162
	v_rcp_f32_e32 v163, v163
	v_pk_mul_f32 v[160:161], v[164:165], v[160:161] op_sel_hi:[0,1]
	v_pk_mul_f32 v[48:49], v[48:49], v[160:161]
	v_pk_mul_f32 v[162:163], v[164:165], v[162:163] op_sel_hi:[0,1]
	v_pk_mul_f32 v[50:51], v[50:51], v[162:163]
	v_cvt_pk_bf16_f32 v68, v56, v57
	v_cvt_pk_bf16_f32 v69, v58, v59
	v_cvt_pk_bf16_f32 v70, v48, v49
	v_cvt_pk_bf16_f32 v71, v50, v51
	global_store_dwordx4 v[170:171], v[68:71], off
	s_waitcnt lgkmcnt(0)
; __device__ __forceinline__ unsigned pk2(float lo, float hi) { unsigned r; asm volatile("v_cvt_pk_bf16_f32 %0, %1, %2" : "=v"(r) : "v"(lo), "v"(hi)); return r; }
; __device__ __forceinline__ unsigned pk2(float lo, float hi) { return f2bf(lo) | (f2bf(hi) << 16); }
;     __device__ __forceinline__ void epi(const f32x4 (&acc)[2][2][4][2], const Unit& u, int wr, int wc, int fr, int fq) const {
;     ...
;         for (int ai = 0; ai < 2; ++ai)
; #pragma unroll
;             for (int m = 0; m < 4; ++m) {
;                 const int row = row0 + ai * 128 + m * 16; const float rs = rs_lds[((u.pm >> 3) & 1) * 256 + (row & 255)];
;                 const float rs2 = rs * -1.4426950408889634f, rsq = rs * rs;
;                 f32x2 v[4];
; #pragma unroll
;                 for (int n = 0; n < 2; ++n)
; #pragma unroll
;                     for (int jp = 0; jp < 2; ++jp) {
;                         const f32x2 gg = (f32x2){acc[ai][0][m][n][2 * jp], acc[ai][0][m][n][2 * jp + 1]}, uu = (f32x2){acc[ai][1][m][n][2 * jp], acc[ai][1][m][n][2 * jp + 1]};
;                         const f32x2 t = gg * rs2; f32x2 e; e.x = __builtin_amdgcn_exp2f(t.x); e.y = __builtin_amdgcn_exp2f(t.y);
;                         const f32x2 d = e + 1.0f; f32x2 r; r.x = __builtin_amdgcn_rcpf(d.x); r.y = __builtin_amdgcn_rcpf(d.y);
;                         v[n * 2 + jp] = (gg * uu) * (r * rsq);
;                     }
;                 u32x4 w; w.x = pk2(v[0].x, v[0].y); w.y = pk2(v[1].x, v[1].y); w.z = pk2(v[2].x, v[2].y); w.w = pk2(v[3].x, v[3].y);
;                 *(u32x4*)(H + (size_t)row * FF + col0) = w;
	v_mul_f32_e32 v144, 0xbfb8aa3b, v143
	v_mul_f32_e32 v164, v143, v143
	ds_read_b32 v143, v142 offset:640
	v_pk_mul_f32 v[160:161], v[40:41], v[144:145] op_sel_hi:[1,0]
	v_pk_mul_f32 v[162:163], v[42:43], v[144:145] op_sel_hi:[1,0]
	v_exp_f32_e32 v160, v160
	v_exp_f32_e32 v161, v161
	v_exp_f32_e32 v162, v162
	v_exp_f32_e32 v163, v163
	v_pk_mul_f32 v[40:41], v[40:41], v[44:45]
	v_pk_add_f32 v[160:161], v[160:161], 1.0 op_sel_hi:[1,0]
	v_pk_mul_f32 v[42:43], v[42:43], v[46:47]
	v_pk_add_f32 v[162:163], v[162:163], 1.0 op_sel_hi:[1,0]
	v_rcp_f32_e32 v160, v160
	v_rcp_f32_e32 v161, v161
	v_rcp_f32_e32 v162, v162
	v_rcp_f32_e32 v163, v163
	v_pk_mul_f32 v[160:161], v[164:165], v[160:161] op_sel_hi:[0,1]
	v_pk_mul_f32 v[40:41], v[40:41], v[160:161]
	v_pk_mul_f32 v[162:163], v[164:165], v[162:163] op_sel_hi:[0,1]
	v_pk_mul_f32 v[42:43], v[42:43], v[162:163]
	v_pk_mul_f32 v[160:161], v[32:33], v[144:145] op_sel_hi:[1,0]
	v_pk_mul_f32 v[162:163], v[34:35], v[144:145] op_sel_hi:[1,0]
	v_exp_f32_e32 v160, v160
	v_exp_f32_e32 v161, v161
	v_exp_f32_e32 v162, v162
	v_exp_f32_e32 v163, v163
	v_pk_mul_f32 v[32:33], v[32:33], v[36:37]
	v_pk_add_f32 v[160:161], v[160:161], 1.0 op_sel_hi:[1,0]
	v_pk_mul_f32 v[34:35], v[34:35], v[38:39]
	v_pk_add_f32 v[162:163], v[162:163], 1.0 op_sel_hi:[1,0]
	v_rcp_f32_e32 v160, v160
	v_rcp_f32_e32 v161, v161
	v_rcp_f32_e32 v162, v162
	v_rcp_f32_e32 v163, v163
	v_pk_mul_f32 v[160:161], v[164:165], v[160:161] op_sel_hi:[0,1]
	v_pk_mul_f32 v[32:33], v[32:33], v[160:161]
	v_pk_mul_f32 v[162:163], v[164:165], v[162:163] op_sel_hi:[0,1]
	v_pk_mul_f32 v[34:35], v[34:35], v[162:163]
	v_cvt_pk_bf16_f32 v44, v40, v41
	v_cvt_pk_bf16_f32 v45, v42, v43
	v_cvt_pk_bf16_f32 v46, v32, v33
	v_cvt_pk_bf16_f32 v47, v34, v35
	v_lshl_add_u64 v[170:171], v[170:171], 0, v[168:169]
	global_store_dwordx4 v[170:171], v[44:47], off
	s_waitcnt lgkmcnt(0)
	v_mul_f32_e32 v144, 0xbfb8aa3b, v143
	v_mul_f32_e32 v164, v143, v143
	ds_read_b32 v143, v142 offset:704
	v_pk_mul_f32 v[160:161], v[24:25], v[144:145] op_sel_hi:[1,0]
	v_pk_mul_f32 v[162:163], v[26:27], v[144:145] op_sel_hi:[1,0]
	v_exp_f32_e32 v160, v160
	v_exp_f32_e32 v161, v161
	v_exp_f32_e32 v162, v162
	v_exp_f32_e32 v163, v163
	v_pk_mul_f32 v[24:25], v[24:25], v[28:29]
	v_pk_add_f32 v[160:161], v[160:161], 1.0 op_sel_hi:[1,0]
	v_pk_mul_f32 v[26:27], v[26:27], v[30:31]
	v_pk_add_f32 v[162:163], v[162:163], 1.0 op_sel_hi:[1,0]
	v_rcp_f32_e32 v160, v160
	v_rcp_f32_e32 v161, v161
	v_rcp_f32_e32 v162, v162
	v_rcp_f32_e32 v163, v163
	v_pk_mul_f32 v[160:161], v[164:165], v[160:161] op_sel_hi:[0,1]
	v_pk_mul_f32 v[24:25], v[24:25], v[160:161]
	v_pk_mul_f32 v[162:163], v[164:165], v[162:163] op_sel_hi:[0,1]
	v_pk_mul_f32 v[26:27], v[26:27], v[162:163]
	v_pk_mul_f32 v[160:161], v[16:17], v[144:145] op_sel_hi:[1,0]
	v_pk_mul_f32 v[162:163], v[18:19], v[144:145] op_sel_hi:[1,0]
	v_exp_f32_e32 v160, v160
	v_exp_f32_e32 v161, v161
	v_exp_f32_e32 v162, v162
	v_exp_f32_e32 v163, v163
	v_pk_mul_f32 v[16:17], v[16:17], v[20:21]
	v_pk_add_f32 v[160:161], v[160:161], 1.0 op_sel_hi:[1,0]
	v_pk_mul_f32 v[18:19], v[18:19], v[22:23]
	v_pk_add_f32 v[162:163], v[162:163], 1.0 op_sel_hi:[1,0]
	v_rcp_f32_e32 v160, v160
	v_rcp_f32_e32 v161, v161
	v_rcp_f32_e32 v162, v162
	v_rcp_f32_e32 v163, v163
	v_pk_mul_f32 v[160:161], v[164:165], v[160:161] op_sel_hi:[0,1]
	v_pk_mul_f32 v[16:17], v[16:17], v[160:161]
	v_pk_mul_f32 v[162:163], v[164:165], v[162:163] op_sel_hi:[0,1]
	v_pk_mul_f32 v[18:19], v[18:19], v[162:163]
	v_cvt_pk_bf16_f32 v28, v24, v25
	v_cvt_pk_bf16_f32 v29, v26, v27
	v_cvt_pk_bf16_f32 v30, v16, v17
	v_cvt_pk_bf16_f32 v31, v18, v19
	v_lshl_add_u64 v[170:171], v[170:171], 0, v[168:169]
	global_store_dwordx4 v[170:171], v[28:31], off
	s_waitcnt lgkmcnt(0)
	v_mul_f32_e32 v144, 0xbfb8aa3b, v143
	v_mul_f32_e32 v164, v143, v143
	ds_read_b32 v143, v142 offset:0
	v_pk_mul_f32 v[160:161], v[8:9], v[144:145] op_sel_hi:[1,0]
	v_pk_mul_f32 v[162:163], v[10:11], v[144:145] op_sel_hi:[1,0]
	v_exp_f32_e32 v160, v160
	v_exp_f32_e32 v161, v161
	v_exp_f32_e32 v162, v162
	v_exp_f32_e32 v163, v163
	v_pk_mul_f32 v[8:9], v[8:9], v[12:13]
	v_pk_add_f32 v[160:161], v[160:161], 1.0 op_sel_hi:[1,0]
	v_pk_mul_f32 v[10:11], v[10:11], v[14:15]
	v_pk_add_f32 v[162:163], v[162:163], 1.0 op_sel_hi:[1,0]
	v_rcp_f32_e32 v160, v160
	v_rcp_f32_e32 v161, v161
	v_rcp_f32_e32 v162, v162
	v_rcp_f32_e32 v163, v163
	v_pk_mul_f32 v[160:161], v[164:165], v[160:161] op_sel_hi:[0,1]
	v_pk_mul_f32 v[8:9], v[8:9], v[160:161]
	v_pk_mul_f32 v[162:163], v[164:165], v[162:163] op_sel_hi:[0,1]
	v_pk_mul_f32 v[10:11], v[10:11], v[162:163]
	v_pk_mul_f32 v[160:161], v[0:1], v[144:145] op_sel_hi:[1,0]
	v_pk_mul_f32 v[162:163], v[2:3], v[144:145] op_sel_hi:[1,0]
	v_exp_f32_e32 v160, v160
	v_exp_f32_e32 v161, v161
	v_exp_f32_e32 v162, v162
	v_exp_f32_e32 v163, v163
	v_pk_mul_f32 v[0:1], v[0:1], v[4:5]
	v_pk_add_f32 v[160:161], v[160:161], 1.0 op_sel_hi:[1,0]
	v_pk_mul_f32 v[2:3], v[2:3], v[6:7]
	v_pk_add_f32 v[162:163], v[162:163], 1.0 op_sel_hi:[1,0]
	v_rcp_f32_e32 v160, v160
	v_rcp_f32_e32 v161, v161
	v_rcp_f32_e32 v162, v162
	v_rcp_f32_e32 v163, v163
	v_pk_mul_f32 v[160:161], v[164:165], v[160:161] op_sel_hi:[0,1]
	v_pk_mul_f32 v[0:1], v[0:1], v[160:161]
	v_pk_mul_f32 v[162:163], v[164:165], v[162:163] op_sel_hi:[0,1]
	v_pk_mul_f32 v[2:3], v[2:3], v[162:163]
	v_cvt_pk_bf16_f32 v12, v8, v9
	v_cvt_pk_bf16_f32 v13, v10, v11
	v_cvt_pk_bf16_f32 v14, v0, v1
	v_cvt_pk_bf16_f32 v15, v2, v3
	v_lshl_add_u64 v[170:171], v[170:171], 0, v[168:169]
	global_store_dwordx4 v[170:171], v[12:15], off
	s_and_b64 vcc, exec, s[14:15]
	s_cbranch_vccnz .Lgu_nh_229
	ds_read_b128 v[0:3], v152
	ds_read_b128 v[4:7], v152 offset:1024
	ds_read_b128 v[8:11], v152 offset:2048
	ds_read_b128 v[12:15], v152 offset:3072
	s_add_u32 s34, s20, 0x40080
	s_addc_u32 s35, s21, 0
	s_mov_b32 m0, s47
	v_lshl_add_u64 v[48:49], s[34:35], 0, v[136:137]
	ds_read_b128 v[16:19], v153
	ds_read_b128 v[20:23], v153 offset:1024
	ds_read_b128 v[24:27], v153 offset:2048
	ds_read_b128 v[28:31], v153 offset:3072
	ds_read_b128 v[32:35], v153 offset:4096
	ds_read_b128 v[36:39], v153 offset:5120
	ds_read_b128 v[40:43], v153 offset:6144
	ds_read_b128 v[44:47], v153 offset:7168
	global_load_lds_dwordx4 v[48:49], off
	s_mov_b32 m0, s48
	v_lshl_add_u64 v[48:49], s[34:35], 0, v[132:133]
	global_load_lds_dwordx4 v[48:49], off
; __device__ __forceinline__ unsigned pk2(float lo, float hi) { unsigned r; asm volatile("v_cvt_pk_bf16_f32 %0, %1, %2" : "=v"(r) : "v"(lo), "v"(hi)); return r; }
; __device__ __forceinline__ unsigned pk2(float lo, float hi) { return f2bf(lo) | (f2bf(hi) << 16); }
;     __device__ __forceinline__ void epi(const f32x4 (&acc)[2][2][4][2], const Unit& u, int wr, int wc, int fr, int fq) const {
;     ...
;         for (int ai = 0; ai < 2; ++ai)
; #pragma unroll
;             for (int m = 0; m < 4; ++m) {
;                 const int row = row0 + ai * 128 + m * 16; const float rs = rs_lds[((u.pm >> 3) & 1) * 256 + (row & 255)];
;                 const float rs2 = rs * -1.4426950408889634f, rsq = rs * rs;
;                 f32x2 v[4];
; #pragma unroll
;                 for (int n = 0; n < 2; ++n)
; #pragma unroll
;                     for (int jp = 0; jp < 2; ++jp) {
;                         const f32x2 gg = (f32x2){acc[ai][0][m][n][2 * jp], acc[ai][0][m][n][2 * jp + 1]}, uu = (f32x2){acc[ai][1][m][n][2 * jp], acc[ai][1][m][n][2 * jp + 1]};
;                         const f32x2 t = gg * rs2; f32x2 e; e.x = __builtin_amdgcn_exp2f(t.x); e.y = __builtin_amdgcn_exp2f(t.y);
;                         const f32x2 d = e + 1.0f; f32x2 r; r.x = __builtin_amdgcn_rcpf(d.x); r.y = __builtin_amdgcn_rcpf(d.y);
;                         v[n * 2 + jp] = (gg * uu) * (r * rsq);
;                     }
;                 u32x4 w; w.x = pk2(v[0].x, v[0].y); w.y = pk2(v[1].x, v[1].y); w.z = pk2(v[2].x, v[2].y); w.w = pk2(v[3].x, v[3].y);
;                 *(u32x4*)(H + (size_t)row * FF + col0) = w;
.Lgu_nh_229:
	s_waitcnt lgkmcnt(0)
	v_mul_f32_e32 v144, 0xbfb8aa3b, v143
	v_mul_f32_e32 v164, v143, v143
	ds_read_b32 v143, v142 offset:64
	v_pk_mul_f32 v[160:161], v[120:121], v[144:145] op_sel_hi:[1,0]
	v_pk_mul_f32 v[162:163], v[122:123], v[144:145] op_sel_hi:[1,0]
	v_exp_f32_e32 v160, v160
	v_exp_f32_e32 v161, v161
	v_exp_f32_e32 v162, v162
	v_exp_f32_e32 v163, v163
	v_pk_mul_f32 v[120:121], v[120:121], v[124:125]
	v_pk_add_f32 v[160:161], v[160:161], 1.0 op_sel_hi:[1,0]
	v_pk_mul_f32 v[122:123], v[122:123], v[126:127]
	v_pk_add_f32 v[162:163], v[162:163], 1.0 op_sel_hi:[1,0]
	v_rcp_f32_e32 v160, v160
	v_rcp_f32_e32 v161, v161
	v_rcp_f32_e32 v162, v162
	v_rcp_f32_e32 v163, v163
	v_pk_mul_f32 v[160:161], v[164:165], v[160:161] op_sel_hi:[0,1]
	v_pk_mul_f32 v[120:121], v[120:121], v[160:161]
	v_pk_mul_f32 v[162:163], v[164:165], v[162:163] op_sel_hi:[0,1]
	v_pk_mul_f32 v[122:123], v[122:123], v[162:163]
	v_pk_mul_f32 v[160:161], v[112:113], v[144:145] op_sel_hi:[1,0]
	v_pk_mul_f32 v[162:163], v[114:115], v[144:145] op_sel_hi:[1,0]
	v_exp_f32_e32 v160, v160
	v_exp_f32_e32 v161, v161
	v_exp_f32_e32 v162, v162
	v_exp_f32_e32 v163, v163
	v_pk_mul_f32 v[112:113], v[112:113], v[116:117]
	v_pk_add_f32 v[160:161], v[160:161], 1.0 op_sel_hi:[1,0]
	v_pk_mul_f32 v[114:115], v[114:115], v[118:119]
	v_pk_add_f32 v[162:163], v[162:163], 1.0 op_sel_hi:[1,0]
	v_rcp_f32_e32 v160, v160
	v_rcp_f32_e32 v161, v161
	v_rcp_f32_e32 v162, v162
	v_rcp_f32_e32 v163, v163
	v_pk_mul_f32 v[160:161], v[164:165], v[160:161] op_sel_hi:[0,1]
	v_pk_mul_f32 v[112:113], v[112:113], v[160:161]
	v_pk_mul_f32 v[162:163], v[164:165], v[162:163] op_sel_hi:[0,1]
	v_pk_mul_f32 v[114:115], v[114:115], v[162:163]
	v_cvt_pk_bf16_f32 v124, v120, v121
	v_cvt_pk_bf16_f32 v125, v122, v123
	v_cvt_pk_bf16_f32 v126, v112, v113
	v_cvt_pk_bf16_f32 v127, v114, v115
	global_store_dwordx4 v[166:167], v[124:127], off
	s_waitcnt lgkmcnt(0)
	v_mul_f32_e32 v144, 0xbfb8aa3b, v143
	v_mul_f32_e32 v164, v143, v143
	ds_read_b32 v143, v142 offset:128
	v_pk_mul_f32 v[160:161], v[104:105], v[144:145] op_sel_hi:[1,0]
	v_pk_mul_f32 v[162:163], v[106:107], v[144:145] op_sel_hi:[1,0]
	v_exp_f32_e32 v160, v160
	v_exp_f32_e32 v161, v161
	v_exp_f32_e32 v162, v162
	v_exp_f32_e32 v163, v163
	v_pk_mul_f32 v[104:105], v[104:105], v[108:109]
	v_pk_add_f32 v[160:161], v[160:161], 1.0 op_sel_hi:[1,0]
	v_pk_mul_f32 v[106:107], v[106:107], v[110:111]
	v_pk_add_f32 v[162:163], v[162:163], 1.0 op_sel_hi:[1,0]
	v_rcp_f32_e32 v160, v160
	v_rcp_f32_e32 v161, v161
	v_rcp_f32_e32 v162, v162
	v_rcp_f32_e32 v163, v163
	v_pk_mul_f32 v[160:161], v[164:165], v[160:161] op_sel_hi:[0,1]
	v_pk_mul_f32 v[104:105], v[104:105], v[160:161]
	v_pk_mul_f32 v[162:163], v[164:165], v[162:163] op_sel_hi:[0,1]
	v_pk_mul_f32 v[106:107], v[106:107], v[162:163]
	v_pk_mul_f32 v[160:161], v[96:97], v[144:145] op_sel_hi:[1,0]
	v_pk_mul_f32 v[162:163], v[98:99], v[144:145] op_sel_hi:[1,0]
	v_exp_f32_e32 v160, v160
	v_exp_f32_e32 v161, v161
	v_exp_f32_e32 v162, v162
	v_exp_f32_e32 v163, v163
	v_pk_mul_f32 v[96:97], v[96:97], v[100:101]
	v_pk_add_f32 v[160:161], v[160:161], 1.0 op_sel_hi:[1,0]
	v_pk_mul_f32 v[98:99], v[98:99], v[102:103]
	v_pk_add_f32 v[162:163], v[162:163], 1.0 op_sel_hi:[1,0]
	v_rcp_f32_e32 v160, v160
	v_rcp_f32_e32 v161, v161
	v_rcp_f32_e32 v162, v162
	v_rcp_f32_e32 v163, v163
	v_pk_mul_f32 v[160:161], v[164:165], v[160:161] op_sel_hi:[0,1]
	v_pk_mul_f32 v[96:97], v[96:97], v[160:161]
	v_pk_mul_f32 v[162:163], v[164:165], v[162:163] op_sel_hi:[0,1]
	v_pk_mul_f32 v[98:99], v[98:99], v[162:163]
	v_cvt_pk_bf16_f32 v108, v104, v105
	v_cvt_pk_bf16_f32 v109, v106, v107
	v_cvt_pk_bf16_f32 v110, v96, v97
	v_cvt_pk_bf16_f32 v111, v98, v99
	v_lshl_add_u64 v[166:167], v[166:167], 0, v[168:169]
	global_store_dwordx4 v[166:167], v[108:111], off
	s_waitcnt lgkmcnt(0)
; __device__ __forceinline__ unsigned pk2(float lo, float hi) { unsigned r; asm volatile("v_cvt_pk_bf16_f32 %0, %1, %2" : "=v"(r) : "v"(lo), "v"(hi)); return r; }
; __device__ __forceinline__ unsigned pk2(float lo, float hi) { return f2bf(lo) | (f2bf(hi) << 16); }
;     ...
;         p.epi(acc, cur, wr, wc, fr, fq);
;         if (!has_next) break;
;         cur = nxt; cA = nA; cB = nB; cA2 = nA2; cB2 = nB2; ++ui;
;     __device__ __forceinline__ void epi(const f32x4 (&acc)[2][2][4][2], const Unit& u, int wr, int wc, int fr, int fq) const {
;     ...
;         for (int ai = 0; ai < 2; ++ai)
; #pragma unroll
;             for (int m = 0; m < 4; ++m) {
;                 const int row = row0 + ai * 128 + m * 16; const float rs = rs_lds[((u.pm >> 3) & 1) * 256 + (row & 255)];
;                 const float rs2 = rs * -1.4426950408889634f, rsq = rs * rs;
;                 f32x2 v[4];
; #pragma unroll
;                 for (int n = 0; n < 2; ++n)
; #pragma unroll
;                     for (int jp = 0; jp < 2; ++jp) {
;                         const f32x2 gg = (f32x2){acc[ai][0][m][n][2 * jp], acc[ai][0][m][n][2 * jp + 1]}, uu = (f32x2){acc[ai][1][m][n][2 * jp], acc[ai][1][m][n][2 * jp + 1]};
;                         const f32x2 t = gg * rs2; f32x2 e; e.x = __builtin_amdgcn_exp2f(t.x); e.y = __builtin_amdgcn_exp2f(t.y);
;                         const f32x2 d = e + 1.0f; f32x2 r; r.x = __builtin_amdgcn_rcpf(d.x); r.y = __builtin_amdgcn_rcpf(d.y);
;                         v[n * 2 + jp] = (gg * uu) * (r * rsq);
;                     }
;                 u32x4 w; w.x = pk2(v[0].x, v[0].y); w.y = pk2(v[1].x, v[1].y); w.z = pk2(v[2].x, v[2].y); w.w = pk2(v[3].x, v[3].y);
;                 *(u32x4*)(H + (size_t)row * FF + col0) = w;
;             }
;         ch.finish();
	v_mul_f32_e32 v144, 0xbfb8aa3b, v143
	v_mul_f32_e32 v164, v143, v143
	ds_read_b32 v143, v142 offset:192
	v_pk_mul_f32 v[160:161], v[88:89], v[144:145] op_sel_hi:[1,0]
	v_pk_mul_f32 v[162:163], v[90:91], v[144:145] op_sel_hi:[1,0]
	v_exp_f32_e32 v160, v160
	v_exp_f32_e32 v161, v161
	v_exp_f32_e32 v162, v162
	v_exp_f32_e32 v163, v163
	v_pk_mul_f32 v[88:89], v[88:89], v[92:93]
	v_pk_add_f32 v[160:161], v[160:161], 1.0 op_sel_hi:[1,0]
	v_pk_mul_f32 v[90:91], v[90:91], v[94:95]
	v_pk_add_f32 v[162:163], v[162:163], 1.0 op_sel_hi:[1,0]
	v_rcp_f32_e32 v160, v160
	v_rcp_f32_e32 v161, v161
	v_rcp_f32_e32 v162, v162
	v_rcp_f32_e32 v163, v163
	v_pk_mul_f32 v[160:161], v[164:165], v[160:161] op_sel_hi:[0,1]
	v_pk_mul_f32 v[88:89], v[88:89], v[160:161]
	v_pk_mul_f32 v[162:163], v[164:165], v[162:163] op_sel_hi:[0,1]
	v_pk_mul_f32 v[90:91], v[90:91], v[162:163]
	v_pk_mul_f32 v[160:161], v[80:81], v[144:145] op_sel_hi:[1,0]
	v_pk_mul_f32 v[162:163], v[82:83], v[144:145] op_sel_hi:[1,0]
	v_exp_f32_e32 v160, v160
	v_exp_f32_e32 v161, v161
	v_exp_f32_e32 v162, v162
	v_exp_f32_e32 v163, v163
	v_pk_mul_f32 v[80:81], v[80:81], v[84:85]
	v_pk_add_f32 v[160:161], v[160:161], 1.0 op_sel_hi:[1,0]
	v_pk_mul_f32 v[82:83], v[82:83], v[86:87]
	v_pk_add_f32 v[162:163], v[162:163], 1.0 op_sel_hi:[1,0]
	v_rcp_f32_e32 v160, v160
	v_rcp_f32_e32 v161, v161
	v_rcp_f32_e32 v162, v162
	v_rcp_f32_e32 v163, v163
	v_pk_mul_f32 v[160:161], v[164:165], v[160:161] op_sel_hi:[0,1]
	v_pk_mul_f32 v[80:81], v[80:81], v[160:161]
	v_pk_mul_f32 v[162:163], v[164:165], v[162:163] op_sel_hi:[0,1]
	v_pk_mul_f32 v[82:83], v[82:83], v[162:163]
	v_cvt_pk_bf16_f32 v92, v88, v89
	v_cvt_pk_bf16_f32 v93, v90, v91
	v_cvt_pk_bf16_f32 v94, v80, v81
	v_cvt_pk_bf16_f32 v95, v82, v83
	v_lshl_add_u64 v[166:167], v[166:167], 0, v[168:169]
	global_store_dwordx4 v[166:167], v[92:95], off
	s_waitcnt lgkmcnt(0)
	v_mul_f32_e32 v144, 0xbfb8aa3b, v143
	v_mul_f32_e32 v164, v143, v143
	v_pk_mul_f32 v[160:161], v[72:73], v[144:145] op_sel_hi:[1,0]
	v_pk_mul_f32 v[162:163], v[74:75], v[144:145] op_sel_hi:[1,0]
	v_exp_f32_e32 v160, v160
	v_exp_f32_e32 v161, v161
	v_exp_f32_e32 v162, v162
	v_exp_f32_e32 v163, v163
	v_pk_mul_f32 v[72:73], v[72:73], v[76:77]
	v_pk_add_f32 v[160:161], v[160:161], 1.0 op_sel_hi:[1,0]
	v_pk_mul_f32 v[74:75], v[74:75], v[78:79]
	v_pk_add_f32 v[162:163], v[162:163], 1.0 op_sel_hi:[1,0]
	v_rcp_f32_e32 v160, v160
	v_rcp_f32_e32 v161, v161
	v_rcp_f32_e32 v162, v162
	v_rcp_f32_e32 v163, v163
	v_pk_mul_f32 v[160:161], v[164:165], v[160:161] op_sel_hi:[0,1]
	v_pk_mul_f32 v[72:73], v[72:73], v[160:161]
	v_pk_mul_f32 v[162:163], v[164:165], v[162:163] op_sel_hi:[0,1]
	v_pk_mul_f32 v[74:75], v[74:75], v[162:163]
	v_pk_mul_f32 v[160:161], v[60:61], v[144:145] op_sel_hi:[1,0]
	v_pk_mul_f32 v[162:163], v[62:63], v[144:145] op_sel_hi:[1,0]
	v_exp_f32_e32 v160, v160
	v_exp_f32_e32 v161, v161
	v_exp_f32_e32 v162, v162
	v_exp_f32_e32 v163, v163
	v_pk_mul_f32 v[60:61], v[60:61], v[64:65]
	v_pk_add_f32 v[160:161], v[160:161], 1.0 op_sel_hi:[1,0]
	v_pk_mul_f32 v[62:63], v[62:63], v[66:67]
	v_pk_add_f32 v[162:163], v[162:163], 1.0 op_sel_hi:[1,0]
	v_rcp_f32_e32 v160, v160
	v_rcp_f32_e32 v161, v161
	v_rcp_f32_e32 v162, v162
	v_rcp_f32_e32 v163, v163
	v_pk_mul_f32 v[160:161], v[164:165], v[160:161] op_sel_hi:[0,1]
	v_pk_mul_f32 v[60:61], v[60:61], v[160:161]
	v_pk_mul_f32 v[162:163], v[164:165], v[162:163] op_sel_hi:[0,1]
	v_pk_mul_f32 v[62:63], v[62:63], v[162:163]
	v_cvt_pk_bf16_f32 v76, v72, v73
	v_cvt_pk_bf16_f32 v77, v74, v75
	v_cvt_pk_bf16_f32 v78, v60, v61
	v_cvt_pk_bf16_f32 v79, v62, v63
	v_lshl_add_u64 v[166:167], v[166:167], 0, v[168:169]
	global_store_dwordx4 v[166:167], v[76:79], off
	s_mov_b64 s[28:29], s[22:23]
	s_mov_b64 s[26:27], s[20:21]
	s_and_b64 vcc, exec, s[14:15]
	s_cbranch_vccz .Lgu_fp_229
	s_waitcnt vmcnt(0)
	s_cmpk_gt_u32 s38, 0xff
	s_cbranch_scc1 .LBB0_236
	s_barrier
